# P1 REG0 epilogue: rotary cos/sin rows prefetched one row-group ahead (SGPR-base loads into alternating register sets)
# speedup vs baseline: 1.0054x; 1.0054x over previous
; template <int REG>
; DI void epi_inproj(const Params& p, f32x4 (&acc)[2][2][4][2], int pm, int pn, LAS unsigned char* shm) {
;     ...
;       for (int m = 0; m < 4; ++m) { asm volatile("" ::: "memory");
;         const int r = 128 * ai + 64 * wr + 16 * m + fr, t = t0 + r;
;         const float rs = rsr[ai][m];
;         const f32x4 cs = *(const f32x4*)(cosT + t * 64 + 16 * wc + 4 * fq), sn = *(const f32x4*)(sinT + t * 64 + 16 * wc + 4 * fq);
; #pragma unroll
;         for (int bj = 0; bj < 2; ++bj) {
;           const int h = 2 * (pn & 1) + bj;
;           const float sc = fast_exp2((isk ? -1.f : 1.f) * (float)(t & 127) * lg2gamma(h)) * rs;
;           const f32x4 x1 = acc[ai][bj][m][0] * sc, x2 = acc[ai][bj][m][1] * sc;
;           const f32x4 y1 = x1 * cs - x2 * sn, y2 = x2 * cs + x1 * sn;
;           const int d = 16 * wc + 4 * fq;
;           const int tl2 = t & 127, r32 = tl2 & 31;
;           const int frag = isk ? (((tl2 >> 5) * 2 + ((r32 >> 2) & 1)) * 4 + (d >> 5)) : ((tl2 >> 4) * 4 + (d >> 5));
;           const int frl = isk ? ((r32 >> 3) * 4 + (r32 & 3)) : (tl2 & 15);
;           bf16_t* dst = dstb + ((long)((b * 4 + h) * 64 + (t >> 7))) * 16384 + (frag * 64 + ((d >> 3) & 3) * 16 + frl) * 8 + (d & 7);
;           const u32x2 o1 = pk4(y1), o2 = pk4(y2);
;           *(u32x2*)dst = o1; *(u32x2*)(dst + 2 * 512) = o2;
;           if (isk) {
;             LAS unsigned char* tb = shm + 135168 + wid * 1024;
;             LAS bf16_t* w1 = (LAS bf16_t*)(tb + (4 * fq) * 32 + fr * 2);
;             w1[0] = (bf16_t)(o1.x & 0xffff); w1[16] = (bf16_t)(o1.x >> 16); w1[32] = (bf16_t)(o1.y & 0xffff); w1[48] = (bf16_t)(o1.y >> 16);
;             LAS bf16_t* w2 = w1 + 16 * 16;
;             w2[0] = (bf16_t)(o2.x & 0xffff); w2[16] = (bf16_t)(o2.x >> 16); w2[32] = (bf16_t)(o2.y & 0xffff); w2[48] = (bf16_t)(o2.y >> 16);
;             asm volatile("s_waitcnt lgkmcnt(0)" ::: "memory");
;             const int dl = lane >> 1, th = lane & 1;
;             const u32x4 kv = *(const LAS u32x4*)(tb + dl * 32 + th * 16);
;             asm volatile("" ::: "memory");
;             const int dd = dl < 16 ? 16 * wc + dl : 48 + 16 * wc + dl;
;             const int tb0 = t0 + 128 * ai + 64 * wr + 16 * m + 8 * th, tl = tb0 & 127;
;             *(u32x4*)(krt + ((long)((b * 4 + h) * 64 + (tb0 >> 7))) * 16384 + (((dd >> 4) * 4 + (tl >> 5)) * 64 + ((tl >> 3) & 3) * 16 + (dd & 15)) * 8) = kv;
.LBB0_365:
	v_mov_b32_e32 v156, v194
	s_lshl_b32 s6, s8, 8
	v_ashrrev_i32_e32 v169, 6, v156
	v_lshlrev_b32_e32 v170, 4, v169
	v_and_b32_e32 v177, 48, v170
	v_lshrrev_b32_e32 v171, 2, v156
	s_ashr_i32 s7, s6, 31
	v_lshlrev_b32_e32 v148, 2, v177
	v_and_b32_e32 v178, 12, v171
	v_ashrrev_i32_e32 v157, 8, v156
	s_lshl_b64 s[56:57], s[6:7], 2
	v_lshl_add_u64 v[136:137], s[16:17], 0, v[148:149]
	v_lshlrev_b32_e32 v138, 2, v178
	v_mov_b32_e32 v139, v149
	v_and_b32_e32 v168, 15, v156
	s_add_u32 s56, s78, s56
	v_lshlrev_b32_e32 v176, 6, v157
	v_lshl_add_u64 v[152:153], v[136:137], 0, v[138:139]
	v_lshl_add_u64 v[136:137], s[20:21], 0, v[148:149]
	s_addc_u32 s57, s79, s57
	v_lshlrev_b32_e32 v64, 3, v168
	s_and_b32 s59, s6, 0x1f00
	v_lshl_add_u64 v[154:155], v[136:137], 0, v[138:139]
	v_or_b32_e32 v136, v176, v168
	v_lshl_or_b32 v64, v157, 7, v64
	v_add_u32_e32 v148, s59, v136
	v_ashrrev_i32_e32 v65, 31, v64
	v_lshlrev_b32_e32 v136, 6, v148
	v_lshl_add_u64 v[132:133], v[64:65], 2, s[56:57]
	v_ashrrev_i32_e32 v137, 31, v136
	global_load_dwordx4 v[64:67], v[132:133], off offset:16
	s_nop 0
	global_load_dwordx4 v[132:135], v[132:133], off
	v_lshlrev_b64 v[140:141], 2, v[136:137]
	v_lshl_add_u64 v[136:137], v[154:155], 0, v[140:141]
	global_load_dwordx4 v[136:139], v[136:137], off
	v_lshl_add_u64 v[140:141], v[152:153], 0, v[140:141]
	global_load_dwordx4 v[140:143], v[140:141], off
	v_or_b32_e32 v251, v176, v168
	v_add_u32_e32 v251, s59, v251
	v_lshlrev_b32_e32 v251, 8, v251
	v_lshl_add_u32 v251, v177, 2, v251
	v_lshl_add_u32 v251, v178, 2, v251
	v_add_u32_e32 v251, 0x1000, v251
	global_load_dwordx4 v[246:249], v251, s[20:21]
	global_load_dwordx4 v[252:255], v251, s[16:17]
	s_cmp_gt_i32 s0, 1
	s_cselect_b64 s[6:7], -1, 0
	s_and_b64 s[56:57], s[6:7], exec
	s_cselect_b32 s1, s88, 0x2300000
	s_add_u32 s56, s26, s1
	s_addc_u32 s57, s27, 0
	s_lshl_b32 s1, s0, 1
	s_lshr_b32 s8, s8, 3
	s_and_b32 s1, s1, 2
	s_and_b32 s8, s8, 0x3fffffc
	s_cmp_eq_u32 s1, 0
	v_bitop3_b32 v172, v176, s90, v168 bitop3:0xc8
	s_cselect_b64 vcc, -1, 0
	s_or_b32 s1, s1, s8
	v_cvt_f32_ubyte0_e32 v172, v172
	s_lshl_b32 s58, s1, 6
	v_bfe_u32 v174, v170, 5, 1
	v_bfe_u32 v179, v156, 1, 5
	v_cndmask_b32_e64 v186, v172, -v172, s[6:7]
	s_cmp_lt_i32 s0, 2
	v_or_b32_e32 v172, v170, v178
	v_and_b32_e32 v173, 3, v156
	v_and_or_b32 v175, v156, 4, v174
	v_lshl_add_u32 v170, v169, 10, s89
	v_lshlrev_b32_e32 v169, 5, v178
	v_lshrrev_b32_e32 v178, 1, v156
	v_and_b32_e32 v184, 1, v156
	v_or_b32_e32 v156, v177, v179
	v_add3_u32 v177, v179, v177, 48
	v_cmp_gt_u32_e64 s[0:1], 16, v179
	v_lshlrev_b32_e32 v172, 1, v172
	v_and_b32_e32 v172, 48, v172
	v_cndmask_b32_e64 v156, v177, v156, s[0:1]
	v_lshrrev_b32_e32 v177, 2, v156
	v_and_b32_e32 v181, 15, v156
	v_and_or_b32 v156, v178, 4, v173
	v_and_b32_e32 v183, 64, v176
	v_and_b32_e32 v182, 60, v177
	v_cndmask_b32_e64 v156, v168, v156, s[6:7]
	v_ashrrev_i32_e32 v187, 7, v148
	v_lshlrev_b32_e32 v148, 4, v157
	v_cndmask_b32_e32 v177, v163, v164, vcc
	v_or_b32_e32 v196, v172, v156
	v_and_b32_e32 v178, 16, v148
	v_lshrrev_b32_e32 v148, 5, v183
	v_mul_f32_e32 v156, v177, v186
	v_and_b32_e32 v195, 4, v171
	v_lshlrev_b32_e32 v171, 1, v168
	v_or_b32_e32 v148, v182, v148
	v_exp_f32_e32 v188, v156
	v_add3_u32 v169, v170, v169, v171
	v_lshlrev_b32_e32 v171, 4, v184
	v_lshlrev_b32_e32 v148, 6, v148
	v_or3_b32 v185, v148, v171, v181
	v_lshlrev_b32_e32 v148, 4, v185
	v_lshl_add_u64 v[156:157], s[46:47], 0, v[148:149]
	v_lshl_add_u32 v170, v179, 5, v170
	v_add_u32_e32 v179, s59, v176
	v_ashrrev_i32_e32 v180, 7, v179
	s_waitcnt vmcnt(2)
	v_mul_f32_e32 v148, v132, v188
	v_pk_mul_f32 v[126:127], v[126:127], v[148:149] op_sel_hi:[1,0]
	v_pk_mul_f32 v[124:125], v[124:125], v[148:149] op_sel_hi:[1,0]
	v_pk_mul_f32 v[128:129], v[128:129], v[148:149] op_sel_hi:[1,0]
	v_pk_mul_f32 v[130:131], v[130:131], v[148:149] op_sel_hi:[1,0]
	v_pk_mul_f32 v[188:189], v[136:137], v[124:125]
	v_pk_mul_f32 v[190:191], v[138:139], v[126:127]
	v_pk_fma_f32 v[188:189], v[140:141], v[128:129], v[188:189] neg_lo:[0,0,1] neg_hi:[0,0,1]
	v_pk_fma_f32 v[190:191], v[142:143], v[130:131], v[190:191] neg_lo:[0,0,1] neg_hi:[0,0,1]
	v_pk_mul_f32 v[128:129], v[136:137], v[128:129]
	v_pk_mul_f32 v[130:131], v[138:139], v[130:131]
	s_nop 0
	v_pk_fma_f32 v[192:193], v[142:143], v[126:127], v[130:131]
	v_pk_fma_f32 v[126:127], v[140:141], v[124:125], v[128:129]
	v_cndmask_b32_e64 v124, v174, v175, s[6:7]
	v_or_b32_e32 v128, v124, v178
	v_add_u32_e32 v124, s58, v187
	v_ashrrev_i32_e32 v125, 31, v124
	v_lshlrev_b64 v[124:125], 15, v[124:125]
	v_lshlrev_b32_e32 v130, 3, v196
	v_lshl_add_u64 v[124:125], s[56:57], 0, v[124:125]
	v_lshl_or_b32 v148, v128, 9, v130
	v_lshl_add_u64 v[128:129], v[148:149], 1, v[124:125]
	v_lshlrev_b32_e32 v124, 1, v195
	v_mov_b32_e32 v125, v149
	v_lshl_add_u64 v[196:197], v[128:129], 0, v[124:125]
	v_cvt_pk_bf16_f32 v128, v188, v189
	v_cvt_pk_bf16_f32 v129, v190, v191
	v_cvt_pk_bf16_f32 v126, v126, v127
	v_cvt_pk_bf16_f32 v127, v192, v193
	global_store_dwordx2 v[196:197], v[128:129], off
	global_store_dwordx2 v[196:197], v[126:127], off offset:2048
	s_cbranch_scc1 .LBB0_367
	ds_write_b16 v169, v128
	ds_write_b16_d16_hi v169, v128 offset:32
	ds_write_b16 v169, v129 offset:64
	ds_write_b16_d16_hi v169, v129 offset:96
	ds_write_b16 v169, v126 offset:512
	ds_write_b16_d16_hi v169, v126 offset:544
	ds_write_b16 v169, v127 offset:576
	ds_write_b16_d16_hi v169, v127 offset:608
	s_waitcnt lgkmcnt(0)
	v_add_u32_e32 v126, v170, v171
	ds_read_b128 v[126:129], v126
	v_add_u32_e32 v188, s58, v180
	v_ashrrev_i32_e32 v189, 31, v188
	v_lshlrev_b64 v[188:189], 15, v[188:189]
	v_lshl_add_u64 v[188:189], v[156:157], 0, v[188:189]
	s_waitcnt lgkmcnt(0)
	global_store_dwordx4 v[188:189], v[126:129], off nt

; template <int REG>
; DI void epi_inproj(const Params& p, f32x4 (&acc)[2][2][4][2], int pm, int pn, LAS unsigned char* shm) {
;     ...
;       for (int m = 0; m < 4; ++m) { asm volatile("" ::: "memory");
;         const int r = 128 * ai + 64 * wr + 16 * m + fr, t = t0 + r;
;         const float rs = rsr[ai][m];
;         const f32x4 cs = *(const f32x4*)(cosT + t * 64 + 16 * wc + 4 * fq), sn = *(const f32x4*)(sinT + t * 64 + 16 * wc + 4 * fq);
; #pragma unroll
;         for (int bj = 0; bj < 2; ++bj) {
;           const int h = 2 * (pn & 1) + bj;
;           const float sc = fast_exp2((isk ? -1.f : 1.f) * (float)(t & 127) * lg2gamma(h)) * rs;
;           const f32x4 x1 = acc[ai][bj][m][0] * sc, x2 = acc[ai][bj][m][1] * sc;
;           const f32x4 y1 = x1 * cs - x2 * sn, y2 = x2 * cs + x1 * sn;
;           const int d = 16 * wc + 4 * fq;
;           const int tl2 = t & 127, r32 = tl2 & 31;
;           const int frag = isk ? (((tl2 >> 5) * 2 + ((r32 >> 2) & 1)) * 4 + (d >> 5)) : ((tl2 >> 4) * 4 + (d >> 5));
;           const int frl = isk ? ((r32 >> 3) * 4 + (r32 & 3)) : (tl2 & 15);
;           bf16_t* dst = dstb + ((long)((b * 4 + h) * 64 + (t >> 7))) * 16384 + (frag * 64 + ((d >> 3) & 3) * 16 + frl) * 8 + (d & 7);
;           const u32x2 o1 = pk4(y1), o2 = pk4(y2);
;           *(u32x2*)dst = o1; *(u32x2*)(dst + 2 * 512) = o2;
;           if (isk) {
;             LAS unsigned char* tb = shm + 135168 + wid * 1024;
;             LAS bf16_t* w1 = (LAS bf16_t*)(tb + (4 * fq) * 32 + fr * 2);
;             w1[0] = (bf16_t)(o1.x & 0xffff); w1[16] = (bf16_t)(o1.x >> 16); w1[32] = (bf16_t)(o1.y & 0xffff); w1[48] = (bf16_t)(o1.y >> 16);
;             LAS bf16_t* w2 = w1 + 16 * 16;
;             w2[0] = (bf16_t)(o2.x & 0xffff); w2[16] = (bf16_t)(o2.x >> 16); w2[32] = (bf16_t)(o2.y & 0xffff); w2[48] = (bf16_t)(o2.y >> 16);
;             asm volatile("s_waitcnt lgkmcnt(0)" ::: "memory");
;             const int dl = lane >> 1, th = lane & 1;
;             const u32x4 kv = *(const LAS u32x4*)(tb + dl * 32 + th * 16);
;             asm volatile("" ::: "memory");
;             const int dd = dl < 16 ? 16 * wc + dl : 48 + 16 * wc + dl;
;             const int tb0 = t0 + 128 * ai + 64 * wr + 16 * m + 8 * th, tl = tb0 & 127;
;             *(u32x4*)(krt + ((long)((b * 4 + h) * 64 + (tb0 >> 7))) * 16384 + (((dd >> 4) * 4 + (tl >> 5)) * 64 + ((tl >> 3) & 3) * 16 + (dd & 15)) * 8) = kv;
.LBB0_369:
	v_or_b32_e32 v127, 16, v176
	v_or_b32_e32 v128, v127, v168
	v_add_u32_e32 v129, s59, v128
	v_lshlrev_b32_e32 v116, 6, v129
	v_ashrrev_i32_e32 v117, 31, v116
	v_lshlrev_b64 v[116:117], 2, v[116:117]
	v_lshl_add_u64 v[118:119], v[154:155], 0, v[116:117]
	v_lshl_add_u64 v[116:117], v[152:153], 0, v[116:117]
	v_add_u32_e32 v251, 0x1000, v251
	global_load_dwordx4 v[238:241], v251, s[20:21]
	global_load_dwordx4 v[242:245], v251, s[16:17]
	v_bitop3_b32 v131, v127, s91, v168 bitop3:0xc8
	v_cvt_f32_ubyte0_e32 v131, v131
	v_lshrrev_b32_e32 v132, 1, v128
	v_cndmask_b32_e64 v128, v131, -v131, s[6:7]
	v_and_or_b32 v131, v132, 12, v173
	v_mul_f32_e32 v132, v177, v128
	v_exp_f32_e32 v132, v132
	v_lshrrev_b32_e32 v127, 2, v127
	v_and_or_b32 v136, v127, 20, v174
	v_and_or_b32 v137, v127, 16, v175
	v_ashrrev_i32_e32 v127, 7, v129
	v_cndmask_b32_e64 v129, v136, v137, s[6:7]
	v_cndmask_b32_e64 v131, v168, v131, s[6:7]
	v_add_u32_e32 v136, s58, v127
	v_lshlrev_b32_e32 v129, 9, v129
	v_or_b32_e32 v131, v131, v172
	v_ashrrev_i32_e32 v137, 31, v136
	v_mul_f32_e32 v132, v133, v132
	v_lshlrev_b64 v[136:137], 15, v[136:137]
	v_lshl_or_b32 v129, v131, 3, v129
	v_pk_mul_f32 v[114:115], v[114:115], v[132:133] op_sel_hi:[1,0]
	v_pk_mul_f32 v[112:113], v[112:113], v[132:133] op_sel_hi:[1,0]
	v_pk_mul_f32 v[110:111], v[110:111], v[132:133] op_sel_hi:[1,0]
	v_pk_mul_f32 v[108:109], v[108:109], v[132:133] op_sel_hi:[1,0]
	v_lshl_add_u64 v[136:137], s[56:57], 0, v[136:137]
	v_lshlrev_b32_e32 v148, 1, v129
	v_mov_b32_e32 v125, v149
	v_lshl_add_u64 v[136:137], v[136:137], 0, v[148:149]
	s_and_b64 vcc, exec, s[8:9]
	v_lshl_add_u64 v[136:137], v[136:137], 0, v[124:125]
	s_waitcnt vmcnt(7)
	v_pk_mul_f32 v[138:139], v[110:111], v[248:249]
	v_pk_mul_f32 v[140:141], v[108:109], v[246:247]
	v_pk_mul_f32 v[142:143], v[114:115], v[248:249]
	v_pk_mul_f32 v[186:187], v[112:113], v[246:247]
	s_waitcnt vmcnt(6)
	v_pk_fma_f32 v[114:115], v[114:115], v[254:255], v[138:139] neg_lo:[0,0,1] neg_hi:[0,0,1]
	v_pk_fma_f32 v[112:113], v[112:113], v[252:253], v[140:141] neg_lo:[0,0,1] neg_hi:[0,0,1]
	v_pk_fma_f32 v[138:139], v[110:111], v[254:255], v[142:143]
	v_pk_fma_f32 v[108:109], v[108:109], v[252:253], v[186:187]
	v_cvt_pk_bf16_f32 v110, v112, v113
	v_cvt_pk_bf16_f32 v111, v114, v115
	v_cvt_pk_bf16_f32 v108, v108, v109
	v_cvt_pk_bf16_f32 v109, v138, v139
	global_store_dwordx2 v[136:137], v[110:111], off
	global_store_dwordx2 v[136:137], v[108:109], off offset:2048
	s_cbranch_vccnz .LBB0_371
	ds_write_b16 v169, v110
	ds_write_b16_d16_hi v169, v110 offset:32
	ds_write_b16 v169, v111 offset:64
	ds_write_b16_d16_hi v169, v111 offset:96
	ds_write_b16 v169, v108 offset:512
	ds_write_b16_d16_hi v169, v108 offset:544
	ds_write_b16 v169, v109 offset:576
	ds_write_b16_d16_hi v169, v109 offset:608
	s_waitcnt lgkmcnt(0)
	v_add_u32_e32 v108, v170, v171
	ds_read_b128 v[108:111], v108
	v_add_u32_e32 v112, s58, v180
	v_ashrrev_i32_e32 v113, 31, v112
	v_lshlrev_b64 v[112:113], 15, v[112:113]
	v_lshl_add_u64 v[112:113], v[156:157], 0, v[112:113]
	s_waitcnt lgkmcnt(0)
	global_store_dwordx4 v[112:113], v[108:111], off offset:512 nt
.LBB0_371:
	s_nop 1
	v_mul_f32_e32 v108, v126, v128
	v_exp_f32_e32 v108, v108
	s_and_b64 vcc, exec, s[8:9]
	v_mul_f32_e32 v108, v133, v108
	v_pk_mul_f32 v[102:103], v[102:103], v[108:109] op_sel_hi:[1,0]
	v_pk_mul_f32 v[106:107], v[106:107], v[108:109] op_sel_hi:[1,0]
	v_pk_mul_f32 v[104:105], v[104:105], v[108:109] op_sel_hi:[1,0]
	v_pk_mul_f32 v[100:101], v[100:101], v[108:109] op_sel_hi:[1,0]
	v_pk_mul_f32 v[108:109], v[102:103], v[248:249]
	v_pk_mul_f32 v[110:111], v[100:101], v[246:247]
	v_pk_fma_f32 v[108:109], v[106:107], v[254:255], v[108:109] neg_lo:[0,0,1] neg_hi:[0,0,1]
	v_pk_mul_f32 v[106:107], v[106:107], v[248:249]
	v_pk_fma_f32 v[110:111], v[104:105], v[252:253], v[110:111] neg_lo:[0,0,1] neg_hi:[0,0,1]
	v_pk_fma_f32 v[106:107], v[102:103], v[254:255], v[106:107]
	v_add_u32_e32 v102, s0, v127
	v_ashrrev_i32_e32 v103, 31, v102
	v_lshlrev_b64 v[102:103], 15, v[102:103]
	v_pk_mul_f32 v[104:105], v[104:105], v[246:247]
	v_lshl_add_u64 v[102:103], s[56:57], 0, v[102:103]
	v_pk_fma_f32 v[100:101], v[100:101], v[252:253], v[104:105]
	v_lshl_add_u64 v[102:103], v[102:103], 0, v[148:149]
	v_lshl_add_u64 v[104:105], v[102:103], 0, v[124:125]
	v_cvt_pk_bf16_f32 v102, v110, v111
	v_cvt_pk_bf16_f32 v103, v108, v109
	v_cvt_pk_bf16_f32 v100, v100, v101
	v_cvt_pk_bf16_f32 v101, v106, v107
	v_mov_b32_e32 v110, v174
	global_store_dwordx2 v[104:105], v[102:103], off
	global_store_dwordx2 v[104:105], v[100:101], off offset:2048
	s_cbranch_vccnz .LBB0_373
	ds_write_b16 v169, v102
	ds_write_b16_d16_hi v169, v102 offset:32
	ds_write_b16 v169, v103 offset:64
	ds_write_b16_d16_hi v169, v103 offset:96
	ds_write_b16 v169, v100 offset:512
	ds_write_b16_d16_hi v169, v100 offset:544
	ds_write_b16 v169, v101 offset:576
	ds_write_b16_d16_hi v169, v101 offset:608
	s_waitcnt lgkmcnt(0)
	v_add_u32_e32 v100, v170, v171
	ds_read_b128 v[100:103], v100
	v_add_u32_e32 v104, s0, v180
	v_ashrrev_i32_e32 v105, 31, v104
	v_lshlrev_b64 v[104:105], 15, v[104:105]
	v_lshl_add_u64 v[104:105], v[156:157], 0, v[104:105]
	v_mov_b32_e32 v110, v175
	s_waitcnt lgkmcnt(0)
	global_store_dwordx4 v[104:105], v[100:103], off offset:512 nt
; template <int REG>
; DI void epi_inproj(const Params& p, f32x4 (&acc)[2][2][4][2], int pm, int pn, LAS unsigned char* shm) {
;     ...
;       for (int m = 0; m < 4; ++m) { asm volatile("" ::: "memory");
;         const int r = 128 * ai + 64 * wr + 16 * m + fr, t = t0 + r;
;         const float rs = rsr[ai][m];
;         const f32x4 cs = *(const f32x4*)(cosT + t * 64 + 16 * wc + 4 * fq), sn = *(const f32x4*)(sinT + t * 64 + 16 * wc + 4 * fq);
; #pragma unroll
;         for (int bj = 0; bj < 2; ++bj) {
;           const int h = 2 * (pn & 1) + bj;
;           const float sc = fast_exp2((isk ? -1.f : 1.f) * (float)(t & 127) * lg2gamma(h)) * rs;
;           const f32x4 x1 = acc[ai][bj][m][0] * sc, x2 = acc[ai][bj][m][1] * sc;
;           const f32x4 y1 = x1 * cs - x2 * sn, y2 = x2 * cs + x1 * sn;
;           const int d = 16 * wc + 4 * fq;
;           const int tl2 = t & 127, r32 = tl2 & 31;
;           const int frag = isk ? (((tl2 >> 5) * 2 + ((r32 >> 2) & 1)) * 4 + (d >> 5)) : ((tl2 >> 4) * 4 + (d >> 5));
;           const int frl = isk ? ((r32 >> 3) * 4 + (r32 & 3)) : (tl2 & 15);
;           bf16_t* dst = dstb + ((long)((b * 4 + h) * 64 + (t >> 7))) * 16384 + (frag * 64 + ((d >> 3) & 3) * 16 + frl) * 8 + (d & 7);
;           const u32x2 o1 = pk4(y1), o2 = pk4(y2);
;           *(u32x2*)dst = o1; *(u32x2*)(dst + 2 * 512) = o2;
;           if (isk) {
;             LAS unsigned char* tb = shm + 135168 + wid * 1024;
;             LAS bf16_t* w1 = (LAS bf16_t*)(tb + (4 * fq) * 32 + fr * 2);
;             w1[0] = (bf16_t)(o1.x & 0xffff); w1[16] = (bf16_t)(o1.x >> 16); w1[32] = (bf16_t)(o1.y & 0xffff); w1[48] = (bf16_t)(o1.y >> 16);
;             LAS bf16_t* w2 = w1 + 16 * 16;
;             w2[0] = (bf16_t)(o2.x & 0xffff); w2[16] = (bf16_t)(o2.x >> 16); w2[32] = (bf16_t)(o2.y & 0xffff); w2[48] = (bf16_t)(o2.y >> 16);
;             asm volatile("s_waitcnt lgkmcnt(0)" ::: "memory");
;             const int dl = lane >> 1, th = lane & 1;
;             const u32x4 kv = *(const LAS u32x4*)(tb + dl * 32 + th * 16);
;             asm volatile("" ::: "memory");
;             const int dd = dl < 16 ? 16 * wc + dl : 48 + 16 * wc + dl;
;             const int tb0 = t0 + 128 * ai + 64 * wr + 16 * m + 8 * th, tl = tb0 & 127;
;             *(u32x4*)(krt + ((long)((b * 4 + h) * 64 + (tb0 >> 7))) * 16384 + (((dd >> 4) * 4 + (tl >> 5)) * 64 + ((tl >> 3) & 3) * 16 + (dd & 15)) * 8) = kv;
.LBB0_373:
	v_or_b32_e32 v108, 32, v176
	s_nop 0
	v_or_b32_e32 v100, v108, v168
	v_add_u32_e32 v112, s59, v100
	v_lshlrev_b32_e32 v100, 6, v112
	v_ashrrev_i32_e32 v101, 31, v100
	v_lshlrev_b64 v[100:101], 2, v[100:101]
	v_lshl_add_u64 v[102:103], v[154:155], 0, v[100:101]
	v_lshl_add_u64 v[100:101], v[152:153], 0, v[100:101]
	v_add_u32_e32 v251, 0x1000, v251
	global_load_dwordx4 v[246:249], v251, s[20:21]
	global_load_dwordx4 v[252:255], v251, s[16:17]
	v_bitop3_b32 v111, v108, s92, v168 bitop3:0xc8
	v_cvt_f32_ubyte0_e32 v111, v111
	v_cndmask_b32_e64 v111, v111, -v111, s[6:7]
	v_mul_f32_e32 v114, v177, v111
	v_exp_f32_e32 v114, v114
	v_lshrrev_b32_e32 v113, 2, v108
	v_lshlrev_b32_e32 v109, 3, v185
	v_and_or_b32 v113, v113, 24, v110
	v_ashrrev_i32_e32 v110, 7, v112
	v_lshl_or_b32 v148, v109, 1, v167
	v_lshl_or_b32 v113, v113, 9, v130
	v_add_u32_e32 v112, s58, v110
	v_lshl_add_u64 v[108:109], s[46:47], 0, v[148:149]
	v_lshlrev_b32_e32 v148, 1, v113
	v_ashrrev_i32_e32 v113, 31, v112
	v_mul_f32_e32 v114, v134, v114
	v_lshlrev_b64 v[112:113], 15, v[112:113]
	v_pk_mul_f32 v[98:99], v[98:99], v[114:115] op_sel_hi:[1,0]
	v_pk_mul_f32 v[96:97], v[96:97], v[114:115] op_sel_hi:[1,0]
	v_pk_mul_f32 v[94:95], v[94:95], v[114:115] op_sel_hi:[1,0]
	v_pk_mul_f32 v[92:93], v[92:93], v[114:115] op_sel_hi:[1,0]
	v_lshl_add_u64 v[112:113], s[56:57], 0, v[112:113]
	v_mov_b32_e32 v125, v149
	v_lshl_add_u64 v[112:113], v[112:113], 0, v[148:149]
	s_and_b64 vcc, exec, s[8:9]
	v_lshl_add_u64 v[112:113], v[112:113], 0, v[124:125]
	s_waitcnt vmcnt(7)
	v_pk_mul_f32 v[114:115], v[94:95], v[240:241]
	v_pk_mul_f32 v[116:117], v[92:93], v[238:239]
	v_pk_mul_f32 v[118:119], v[98:99], v[240:241]
	v_pk_mul_f32 v[120:121], v[96:97], v[238:239]
	s_waitcnt vmcnt(6)
	v_pk_fma_f32 v[98:99], v[98:99], v[244:245], v[114:115] neg_lo:[0,0,1] neg_hi:[0,0,1]
	v_pk_fma_f32 v[96:97], v[96:97], v[242:243], v[116:117] neg_lo:[0,0,1] neg_hi:[0,0,1]
	v_pk_fma_f32 v[114:115], v[94:95], v[244:245], v[118:119]
	v_pk_fma_f32 v[92:93], v[92:93], v[242:243], v[120:121]
	v_cvt_pk_bf16_f32 v94, v96, v97
	v_cvt_pk_bf16_f32 v95, v98, v99
	v_cvt_pk_bf16_f32 v92, v92, v93
	v_cvt_pk_bf16_f32 v93, v114, v115
	global_store_dwordx2 v[112:113], v[94:95], off
	global_store_dwordx2 v[112:113], v[92:93], off offset:2048
	s_cbranch_vccnz .LBB0_375
	ds_write_b16 v169, v94
	ds_write_b16_d16_hi v169, v94 offset:32
	ds_write_b16 v169, v95 offset:64
	ds_write_b16_d16_hi v169, v95 offset:96
	ds_write_b16 v169, v92 offset:512
	ds_write_b16_d16_hi v169, v92 offset:544
	ds_write_b16 v169, v93 offset:576
	ds_write_b16_d16_hi v169, v93 offset:608
	s_waitcnt lgkmcnt(0)
	v_add_u32_e32 v92, v170, v171
	ds_read_b128 v[92:95], v92
	v_add_u32_e32 v96, s58, v180
	v_ashrrev_i32_e32 v97, 31, v96
	v_lshlrev_b64 v[96:97], 15, v[96:97]
	v_lshl_add_u64 v[96:97], v[108:109], 0, v[96:97]
	s_waitcnt lgkmcnt(0)
	global_store_dwordx4 v[96:97], v[92:95], off nt
.LBB0_375:
	s_nop 1
	v_mul_f32_e32 v92, v126, v111
	v_exp_f32_e32 v92, v92
	s_and_b64 vcc, exec, s[8:9]
	v_mul_f32_e32 v92, v134, v92
	v_pk_mul_f32 v[86:87], v[86:87], v[92:93] op_sel_hi:[1,0]
	v_pk_mul_f32 v[90:91], v[90:91], v[92:93] op_sel_hi:[1,0]
	v_pk_mul_f32 v[88:89], v[88:89], v[92:93] op_sel_hi:[1,0]
	v_pk_mul_f32 v[84:85], v[84:85], v[92:93] op_sel_hi:[1,0]
	v_pk_mul_f32 v[92:93], v[86:87], v[240:241]
	v_pk_mul_f32 v[94:95], v[84:85], v[238:239]
	v_pk_fma_f32 v[92:93], v[90:91], v[244:245], v[92:93] neg_lo:[0,0,1] neg_hi:[0,0,1]
	v_pk_mul_f32 v[90:91], v[90:91], v[240:241]
	v_pk_fma_f32 v[94:95], v[88:89], v[242:243], v[94:95] neg_lo:[0,0,1] neg_hi:[0,0,1]
	v_pk_fma_f32 v[90:91], v[86:87], v[244:245], v[90:91]
	v_add_u32_e32 v86, s0, v110
	v_ashrrev_i32_e32 v87, 31, v86
	v_lshlrev_b64 v[86:87], 15, v[86:87]
	v_pk_mul_f32 v[88:89], v[88:89], v[238:239]
	v_lshl_add_u64 v[86:87], s[56:57], 0, v[86:87]
	v_pk_fma_f32 v[84:85], v[84:85], v[242:243], v[88:89]
	v_lshl_add_u64 v[86:87], v[86:87], 0, v[148:149]
	v_lshl_add_u64 v[88:89], v[86:87], 0, v[124:125]
	v_cvt_pk_bf16_f32 v86, v94, v95
	v_cvt_pk_bf16_f32 v87, v92, v93
	v_cvt_pk_bf16_f32 v84, v84, v85
	v_cvt_pk_bf16_f32 v85, v90, v91
	global_store_dwordx2 v[88:89], v[86:87], off
	global_store_dwordx2 v[88:89], v[84:85], off offset:2048
	s_cbranch_vccnz .LBB0_377
	ds_write_b16 v169, v86
	ds_write_b16_d16_hi v169, v86 offset:32
	ds_write_b16 v169, v87 offset:64
	ds_write_b16_d16_hi v169, v87 offset:96
	ds_write_b16 v169, v84 offset:512
	ds_write_b16_d16_hi v169, v84 offset:544
	ds_write_b16 v169, v85 offset:576
	ds_write_b16_d16_hi v169, v85 offset:608
	s_waitcnt lgkmcnt(0)
	v_add_u32_e32 v84, v170, v171
	ds_read_b128 v[84:87], v84
	v_add_u32_e32 v88, s0, v180
	v_ashrrev_i32_e32 v89, 31, v88
	v_lshlrev_b64 v[88:89], 15, v[88:89]
	v_lshl_add_u64 v[88:89], v[108:109], 0, v[88:89]
	s_waitcnt lgkmcnt(0)
	global_store_dwordx4 v[88:89], v[84:87], off nt
; template <int REG>
; DI void epi_inproj(const Params& p, f32x4 (&acc)[2][2][4][2], int pm, int pn, LAS unsigned char* shm) {
;     ...
;       for (int m = 0; m < 4; ++m) { asm volatile("" ::: "memory");
;         const int r = 128 * ai + 64 * wr + 16 * m + fr, t = t0 + r;
;         const float rs = rsr[ai][m];
;         const f32x4 cs = *(const f32x4*)(cosT + t * 64 + 16 * wc + 4 * fq), sn = *(const f32x4*)(sinT + t * 64 + 16 * wc + 4 * fq);
; #pragma unroll
;         for (int bj = 0; bj < 2; ++bj) {
;           const int h = 2 * (pn & 1) + bj;
;           const float sc = fast_exp2((isk ? -1.f : 1.f) * (float)(t & 127) * lg2gamma(h)) * rs;
;           const f32x4 x1 = acc[ai][bj][m][0] * sc, x2 = acc[ai][bj][m][1] * sc;
;           const f32x4 y1 = x1 * cs - x2 * sn, y2 = x2 * cs + x1 * sn;
;           const int d = 16 * wc + 4 * fq;
;           const int tl2 = t & 127, r32 = tl2 & 31;
;           const int frag = isk ? (((tl2 >> 5) * 2 + ((r32 >> 2) & 1)) * 4 + (d >> 5)) : ((tl2 >> 4) * 4 + (d >> 5));
;           const int frl = isk ? ((r32 >> 3) * 4 + (r32 & 3)) : (tl2 & 15);
;           bf16_t* dst = dstb + ((long)((b * 4 + h) * 64 + (t >> 7))) * 16384 + (frag * 64 + ((d >> 3) & 3) * 16 + frl) * 8 + (d & 7);
;           const u32x2 o1 = pk4(y1), o2 = pk4(y2);
;           *(u32x2*)dst = o1; *(u32x2*)(dst + 2 * 512) = o2;
;           if (isk) {
;             LAS unsigned char* tb = shm + 135168 + wid * 1024;
;             LAS bf16_t* w1 = (LAS bf16_t*)(tb + (4 * fq) * 32 + fr * 2);
;             w1[0] = (bf16_t)(o1.x & 0xffff); w1[16] = (bf16_t)(o1.x >> 16); w1[32] = (bf16_t)(o1.y & 0xffff); w1[48] = (bf16_t)(o1.y >> 16);
;             LAS bf16_t* w2 = w1 + 16 * 16;
;             w2[0] = (bf16_t)(o2.x & 0xffff); w2[16] = (bf16_t)(o2.x >> 16); w2[32] = (bf16_t)(o2.y & 0xffff); w2[48] = (bf16_t)(o2.y >> 16);
;             asm volatile("s_waitcnt lgkmcnt(0)" ::: "memory");
;             const int dl = lane >> 1, th = lane & 1;
;             const u32x4 kv = *(const LAS u32x4*)(tb + dl * 32 + th * 16);
;             asm volatile("" ::: "memory");
;             const int dd = dl < 16 ? 16 * wc + dl : 48 + 16 * wc + dl;
;             const int tb0 = t0 + 128 * ai + 64 * wr + 16 * m + 8 * th, tl = tb0 & 127;
;             *(u32x4*)(krt + ((long)((b * 4 + h) * 64 + (tb0 >> 7))) * 16384 + (((dd >> 4) * 4 + (tl >> 5)) * 64 + ((tl >> 3) & 3) * 16 + (dd & 15)) * 8) = kv;
.LBB0_377:
	v_or_b32_e32 v92, 48, v176
	v_or_b32_e32 v93, v92, v168
	v_add_u32_e32 v94, s59, v93
	v_lshlrev_b32_e32 v84, 6, v94
	v_ashrrev_i32_e32 v85, 31, v84
	v_lshlrev_b64 v[84:85], 2, v[84:85]
	v_lshl_add_u64 v[86:87], v[154:155], 0, v[84:85]
	v_lshl_add_u64 v[84:85], v[152:153], 0, v[84:85]
	v_add_u32_e32 v251, 0x5000, v251
	global_load_dwordx4 v[238:241], v251, s[20:21]
	global_load_dwordx4 v[242:245], v251, s[16:17]
	v_lshlrev_b32_e32 v95, 3, v184
	v_bitop3_b32 v96, v92, s93, v168 bitop3:0xc8
	v_or3_b32 v95, v183, v95, 48
	v_cvt_f32_ubyte0_e32 v96, v96
	v_lshrrev_b32_e32 v98, 5, v95
	v_lshlrev_b32_e32 v99, 1, v95
	v_cndmask_b32_e64 v95, v96, -v96, s[6:7]
	v_or_b32_e32 v96, v182, v98
	v_and_b32_e32 v98, 48, v99
	v_lshlrev_b32_e32 v96, 6, v96
	v_mul_f32_e32 v99, v177, v95
	v_lshrrev_b32_e32 v92, 2, v92
	v_lshrrev_b32_e32 v93, 1, v93
	v_or3_b32 v96, v96, v98, v181
	v_exp_f32_e32 v98, v99
	v_and_or_b32 v97, v92, 28, v174
	v_and_or_b32 v92, v92, 24, v175
	v_and_or_b32 v93, v93, 12, v173
	v_ashrrev_i32_e32 v94, 7, v94
	v_cndmask_b32_e64 v97, v97, v92, s[6:7]
	v_cndmask_b32_e64 v93, v168, v93, s[6:7]
	v_add_u32_e32 v92, s58, v94
	v_lshlrev_b32_e32 v100, 9, v97
	v_or_b32_e32 v101, v93, v172
	v_ashrrev_i32_e32 v93, 31, v92
	v_lshl_or_b32 v99, v101, 3, v100
	v_mul_f32_e32 v98, v135, v98
	v_lshlrev_b32_e32 v148, 4, v96
	v_lshlrev_b64 v[96:97], 15, v[92:93]
	v_pk_mul_f32 v[82:83], v[82:83], v[98:99] op_sel_hi:[1,0]
	v_pk_mul_f32 v[80:81], v[80:81], v[98:99] op_sel_hi:[1,0]
	v_pk_mul_f32 v[78:79], v[78:79], v[98:99] op_sel_hi:[1,0]
	v_pk_mul_f32 v[76:77], v[76:77], v[98:99] op_sel_hi:[1,0]
	v_lshl_add_u64 v[92:93], s[46:47], 0, v[148:149]
	v_lshl_add_u64 v[96:97], s[56:57], 0, v[96:97]
	v_lshlrev_b32_e32 v148, 1, v99
	v_mov_b32_e32 v125, v149
	v_lshl_add_u64 v[96:97], v[96:97], 0, v[148:149]
	s_and_b64 vcc, exec, s[8:9]
	v_lshl_add_u64 v[96:97], v[96:97], 0, v[124:125]
	s_waitcnt vmcnt(7)
	v_pk_mul_f32 v[98:99], v[78:79], v[248:249]
	v_pk_mul_f32 v[100:101], v[76:77], v[246:247]
	v_pk_mul_f32 v[102:103], v[82:83], v[248:249]
	v_pk_mul_f32 v[104:105], v[80:81], v[246:247]
	s_waitcnt vmcnt(6)
	v_pk_fma_f32 v[82:83], v[82:83], v[254:255], v[98:99] neg_lo:[0,0,1] neg_hi:[0,0,1]
	v_pk_fma_f32 v[80:81], v[80:81], v[252:253], v[100:101] neg_lo:[0,0,1] neg_hi:[0,0,1]
	v_pk_fma_f32 v[98:99], v[78:79], v[254:255], v[102:103]
	v_pk_fma_f32 v[76:77], v[76:77], v[252:253], v[104:105]
	v_cvt_pk_bf16_f32 v78, v80, v81
	v_cvt_pk_bf16_f32 v79, v82, v83
	v_cvt_pk_bf16_f32 v76, v76, v77
	v_cvt_pk_bf16_f32 v77, v98, v99
	global_store_dwordx2 v[96:97], v[78:79], off
	global_store_dwordx2 v[96:97], v[76:77], off offset:2048
	s_cbranch_vccnz .LBB0_379
	ds_write_b16 v169, v78
	ds_write_b16_d16_hi v169, v78 offset:32
	ds_write_b16 v169, v79 offset:64
	ds_write_b16_d16_hi v169, v79 offset:96
	ds_write_b16 v169, v76 offset:512
	ds_write_b16_d16_hi v169, v76 offset:544
	ds_write_b16 v169, v77 offset:576
	ds_write_b16_d16_hi v169, v77 offset:608
	s_waitcnt lgkmcnt(0)
	v_add_u32_e32 v76, v170, v171
	ds_read_b128 v[76:79], v76
	v_add_u32_e32 v80, s58, v180
	v_ashrrev_i32_e32 v81, 31, v80
	v_lshlrev_b64 v[80:81], 15, v[80:81]
	v_lshl_add_u64 v[80:81], v[92:93], 0, v[80:81]
	s_waitcnt lgkmcnt(0)
	global_store_dwordx4 v[80:81], v[76:79], off nt
.LBB0_379:
	s_nop 1
	v_mul_f32_e32 v76, v126, v95
	v_exp_f32_e32 v76, v76
	s_and_b64 vcc, exec, s[8:9]
	v_mul_f32_e32 v76, v135, v76
	v_pk_mul_f32 v[70:71], v[70:71], v[76:77] op_sel_hi:[1,0]
	v_pk_mul_f32 v[74:75], v[74:75], v[76:77] op_sel_hi:[1,0]
	v_pk_mul_f32 v[72:73], v[72:73], v[76:77] op_sel_hi:[1,0]
	v_pk_mul_f32 v[68:69], v[68:69], v[76:77] op_sel_hi:[1,0]
	v_pk_mul_f32 v[76:77], v[70:71], v[248:249]
	v_pk_mul_f32 v[78:79], v[68:69], v[246:247]
	v_pk_fma_f32 v[76:77], v[74:75], v[254:255], v[76:77] neg_lo:[0,0,1] neg_hi:[0,0,1]
	v_pk_mul_f32 v[74:75], v[74:75], v[248:249]
	v_pk_fma_f32 v[78:79], v[72:73], v[252:253], v[78:79] neg_lo:[0,0,1] neg_hi:[0,0,1]
	v_pk_fma_f32 v[74:75], v[70:71], v[254:255], v[74:75]
	v_add_u32_e32 v70, s0, v94
	v_ashrrev_i32_e32 v71, 31, v70
	v_lshlrev_b64 v[70:71], 15, v[70:71]
	v_pk_mul_f32 v[72:73], v[72:73], v[246:247]
	v_lshl_add_u64 v[70:71], s[56:57], 0, v[70:71]
	v_pk_fma_f32 v[68:69], v[68:69], v[252:253], v[72:73]
	v_lshl_add_u64 v[70:71], v[70:71], 0, v[148:149]
	v_lshl_add_u64 v[72:73], v[70:71], 0, v[124:125]
	v_cvt_pk_bf16_f32 v70, v78, v79
	v_cvt_pk_bf16_f32 v71, v76, v77
	v_cvt_pk_bf16_f32 v68, v68, v69
	v_cvt_pk_bf16_f32 v69, v74, v75
	v_mov_b32_e32 v76, v174
	global_store_dwordx2 v[72:73], v[70:71], off
	global_store_dwordx2 v[72:73], v[68:69], off offset:2048
	s_cbranch_vccnz .LBB0_381
	ds_write_b16 v169, v70
	ds_write_b16_d16_hi v169, v70 offset:32
	ds_write_b16 v169, v71 offset:64
	ds_write_b16_d16_hi v169, v71 offset:96
	ds_write_b16 v169, v68 offset:512
	ds_write_b16_d16_hi v169, v68 offset:544
	ds_write_b16 v169, v69 offset:576
	ds_write_b16_d16_hi v169, v69 offset:608
	s_waitcnt lgkmcnt(0)
	v_add_u32_e32 v68, v170, v171
	ds_read_b128 v[68:71], v68
	v_add_u32_e32 v72, s0, v180
	v_ashrrev_i32_e32 v73, 31, v72
	v_lshlrev_b64 v[72:73], 15, v[72:73]
	v_lshl_add_u64 v[72:73], v[92:93], 0, v[72:73]
	v_mov_b32_e32 v76, v175
	s_waitcnt lgkmcnt(0)
	global_store_dwordx4 v[72:73], v[68:71], off nt
; template <int REG>
; DI void epi_inproj(const Params& p, f32x4 (&acc)[2][2][4][2], int pm, int pn, LAS unsigned char* shm) {
;     ...
;       for (int m = 0; m < 4; ++m) { asm volatile("" ::: "memory");
;         const int r = 128 * ai + 64 * wr + 16 * m + fr, t = t0 + r;
;         const float rs = rsr[ai][m];
;         const f32x4 cs = *(const f32x4*)(cosT + t * 64 + 16 * wc + 4 * fq), sn = *(const f32x4*)(sinT + t * 64 + 16 * wc + 4 * fq);
; #pragma unroll
;         for (int bj = 0; bj < 2; ++bj) {
;           const int h = 2 * (pn & 1) + bj;
;           const float sc = fast_exp2((isk ? -1.f : 1.f) * (float)(t & 127) * lg2gamma(h)) * rs;
;           const f32x4 x1 = acc[ai][bj][m][0] * sc, x2 = acc[ai][bj][m][1] * sc;
;           const f32x4 y1 = x1 * cs - x2 * sn, y2 = x2 * cs + x1 * sn;
;           const int d = 16 * wc + 4 * fq;
;           const int tl2 = t & 127, r32 = tl2 & 31;
;           const int frag = isk ? (((tl2 >> 5) * 2 + ((r32 >> 2) & 1)) * 4 + (d >> 5)) : ((tl2 >> 4) * 4 + (d >> 5));
;           const int frl = isk ? ((r32 >> 3) * 4 + (r32 & 3)) : (tl2 & 15);
;           bf16_t* dst = dstb + ((long)((b * 4 + h) * 64 + (t >> 7))) * 16384 + (frag * 64 + ((d >> 3) & 3) * 16 + frl) * 8 + (d & 7);
;           const u32x2 o1 = pk4(y1), o2 = pk4(y2);
;           *(u32x2*)dst = o1; *(u32x2*)(dst + 2 * 512) = o2;
;           if (isk) {
;             LAS unsigned char* tb = shm + 135168 + wid * 1024;
;             LAS bf16_t* w1 = (LAS bf16_t*)(tb + (4 * fq) * 32 + fr * 2);
;             w1[0] = (bf16_t)(o1.x & 0xffff); w1[16] = (bf16_t)(o1.x >> 16); w1[32] = (bf16_t)(o1.y & 0xffff); w1[48] = (bf16_t)(o1.y >> 16);
;             LAS bf16_t* w2 = w1 + 16 * 16;
;             w2[0] = (bf16_t)(o2.x & 0xffff); w2[16] = (bf16_t)(o2.x >> 16); w2[32] = (bf16_t)(o2.y & 0xffff); w2[48] = (bf16_t)(o2.y >> 16);
;             asm volatile("s_waitcnt lgkmcnt(0)" ::: "memory");
;             const int dl = lane >> 1, th = lane & 1;
;             const u32x4 kv = *(const LAS u32x4*)(tb + dl * 32 + th * 16);
;             asm volatile("" ::: "memory");
;             const int dd = dl < 16 ? 16 * wc + dl : 48 + 16 * wc + dl;
;             const int tb0 = t0 + 128 * ai + 64 * wr + 16 * m + 8 * th, tl = tb0 & 127;
;             *(u32x4*)(krt + ((long)((b * 4 + h) * 64 + (tb0 >> 7))) * 16384 + (((dd >> 4) * 4 + (tl >> 5)) * 64 + ((tl >> 3) & 3) * 16 + (dd & 15)) * 8) = kv;
.LBB0_381:
	v_add3_u32 v77, v176, v168, s94
	v_add_u32_e32 v78, s59, v77
	v_lshlrev_b32_e32 v68, 6, v78
	v_ashrrev_i32_e32 v69, 31, v68
	v_lshlrev_b64 v[68:69], 2, v[68:69]
	v_lshl_add_u64 v[70:71], v[154:155], 0, v[68:69]
	v_lshl_add_u64 v[68:69], v[152:153], 0, v[68:69]
	v_add_u32_e32 v251, 0x1000, v251
	global_load_dwordx4 v[246:249], v251, s[20:21]
	global_load_dwordx4 v[252:255], v251, s[16:17]
	v_add_u32_e32 v79, 0x80, v179
	v_add_u32_e32 v80, v76, v178
	v_and_b32_e32 v77, 0x4f, v77
	v_ashrrev_i32_e32 v76, 7, v79
	v_lshl_or_b32 v79, v80, 9, v130
	v_cvt_f32_ubyte0_e32 v80, v77
	v_ashrrev_i32_e32 v77, 7, v78
	v_cndmask_b32_e64 v78, v80, -v80, s[6:7]
	v_lshlrev_b32_e32 v148, 1, v79
	v_mul_f32_e32 v79, v177, v78
	v_exp_f32_e32 v79, v79
	v_add_u32_e32 v80, s58, v77
	v_ashrrev_i32_e32 v81, 31, v80
	v_lshlrev_b64 v[80:81], 15, v[80:81]
	v_mul_f32_e32 v82, v64, v79
	v_pk_mul_f32 v[60:61], v[60:61], v[82:83] op_sel_hi:[1,0]
	v_pk_mul_f32 v[62:63], v[62:63], v[82:83] op_sel_hi:[1,0]
	v_pk_mul_f32 v[56:57], v[56:57], v[82:83] op_sel_hi:[1,0]
	v_pk_mul_f32 v[58:59], v[58:59], v[82:83] op_sel_hi:[1,0]
	v_lshl_add_u64 v[80:81], s[56:57], 0, v[80:81]
	v_mov_b32_e32 v125, v149
	v_lshl_add_u64 v[80:81], v[80:81], 0, v[148:149]
	s_and_b64 vcc, exec, s[8:9]
	v_lshl_add_u64 v[80:81], v[80:81], 0, v[124:125]
	s_waitcnt vmcnt(7)
	v_pk_mul_f32 v[82:83], v[58:59], v[240:241]
	v_pk_mul_f32 v[84:85], v[56:57], v[238:239]
	v_pk_mul_f32 v[86:87], v[62:63], v[240:241]
	v_pk_mul_f32 v[88:89], v[60:61], v[238:239]
	s_waitcnt vmcnt(6)
	v_pk_fma_f32 v[62:63], v[62:63], v[244:245], v[82:83] neg_lo:[0,0,1] neg_hi:[0,0,1]
	v_pk_fma_f32 v[60:61], v[60:61], v[242:243], v[84:85] neg_lo:[0,0,1] neg_hi:[0,0,1]
	v_pk_fma_f32 v[82:83], v[58:59], v[244:245], v[86:87]
	v_pk_fma_f32 v[56:57], v[56:57], v[242:243], v[88:89]
	v_cvt_pk_bf16_f32 v58, v60, v61
	v_cvt_pk_bf16_f32 v59, v62, v63
	v_cvt_pk_bf16_f32 v56, v56, v57
	v_cvt_pk_bf16_f32 v57, v82, v83
	global_store_dwordx2 v[80:81], v[58:59], off
	global_store_dwordx2 v[80:81], v[56:57], off offset:2048
	s_cbranch_vccnz .LBB0_383
	ds_write_b16 v169, v58
	ds_write_b16_d16_hi v169, v58 offset:32
	ds_write_b16 v169, v59 offset:64
	ds_write_b16_d16_hi v169, v59 offset:96
	ds_write_b16 v169, v56 offset:512
	ds_write_b16_d16_hi v169, v56 offset:544
	ds_write_b16 v169, v57 offset:576
	ds_write_b16_d16_hi v169, v57 offset:608
	s_waitcnt lgkmcnt(0)
	v_add_u32_e32 v56, v170, v171
	ds_read_b128 v[56:59], v56
	v_add_u32_e32 v60, s58, v76
	v_ashrrev_i32_e32 v61, 31, v60
	v_lshlrev_b64 v[60:61], 15, v[60:61]
	v_lshl_add_u64 v[60:61], v[156:157], 0, v[60:61]
	s_waitcnt lgkmcnt(0)
	global_store_dwordx4 v[60:61], v[56:59], off nt
.LBB0_383:
	s_nop 1
	v_mul_f32_e32 v56, v126, v78
	v_exp_f32_e32 v56, v56
	s_and_b64 vcc, exec, s[8:9]
	v_mul_f32_e32 v56, v64, v56
	v_pk_mul_f32 v[50:51], v[50:51], v[56:57] op_sel_hi:[1,0]
	v_pk_mul_f32 v[54:55], v[54:55], v[56:57] op_sel_hi:[1,0]
	v_pk_mul_f32 v[52:53], v[52:53], v[56:57] op_sel_hi:[1,0]
	v_pk_mul_f32 v[48:49], v[48:49], v[56:57] op_sel_hi:[1,0]
	v_pk_mul_f32 v[56:57], v[50:51], v[240:241]
	v_pk_mul_f32 v[58:59], v[48:49], v[238:239]
	v_pk_fma_f32 v[56:57], v[54:55], v[244:245], v[56:57] neg_lo:[0,0,1] neg_hi:[0,0,1]
	v_pk_mul_f32 v[54:55], v[54:55], v[240:241]
	v_pk_fma_f32 v[58:59], v[52:53], v[242:243], v[58:59] neg_lo:[0,0,1] neg_hi:[0,0,1]
	v_pk_fma_f32 v[54:55], v[50:51], v[244:245], v[54:55]
	v_add_u32_e32 v50, s0, v77
	v_ashrrev_i32_e32 v51, 31, v50
	v_lshlrev_b64 v[50:51], 15, v[50:51]
	v_pk_mul_f32 v[52:53], v[52:53], v[238:239]
	v_lshl_add_u64 v[50:51], s[56:57], 0, v[50:51]
	v_pk_fma_f32 v[48:49], v[48:49], v[242:243], v[52:53]
	v_lshl_add_u64 v[50:51], v[50:51], 0, v[148:149]
	v_lshl_add_u64 v[52:53], v[50:51], 0, v[124:125]
	v_cvt_pk_bf16_f32 v50, v58, v59
	v_cvt_pk_bf16_f32 v51, v56, v57
	v_cvt_pk_bf16_f32 v48, v48, v49
	v_cvt_pk_bf16_f32 v49, v54, v55
	global_store_dwordx2 v[52:53], v[50:51], off
	global_store_dwordx2 v[52:53], v[48:49], off offset:2048
	s_cbranch_vccnz .LBB0_385
	ds_write_b16 v169, v50
	ds_write_b16_d16_hi v169, v50 offset:32
	ds_write_b16 v169, v51 offset:64
	ds_write_b16_d16_hi v169, v51 offset:96
	ds_write_b16 v169, v48 offset:512
	ds_write_b16_d16_hi v169, v48 offset:544
	ds_write_b16 v169, v49 offset:576
	ds_write_b16_d16_hi v169, v49 offset:608
	s_waitcnt lgkmcnt(0)
	v_add_u32_e32 v48, v170, v171
	ds_read_b128 v[48:51], v48
	v_add_u32_e32 v52, s0, v76
	v_ashrrev_i32_e32 v53, 31, v52
	v_lshlrev_b64 v[52:53], 15, v[52:53]
	v_lshl_add_u64 v[52:53], v[156:157], 0, v[52:53]
	s_waitcnt lgkmcnt(0)
	global_store_dwordx4 v[52:53], v[48:51], off nt
; template <int REG>
; DI void epi_inproj(const Params& p, f32x4 (&acc)[2][2][4][2], int pm, int pn, LAS unsigned char* shm) {
;     ...
;       for (int m = 0; m < 4; ++m) { asm volatile("" ::: "memory");
;         const int r = 128 * ai + 64 * wr + 16 * m + fr, t = t0 + r;
;         const float rs = rsr[ai][m];
;         const f32x4 cs = *(const f32x4*)(cosT + t * 64 + 16 * wc + 4 * fq), sn = *(const f32x4*)(sinT + t * 64 + 16 * wc + 4 * fq);
; #pragma unroll
;         for (int bj = 0; bj < 2; ++bj) {
;           const int h = 2 * (pn & 1) + bj;
;           const float sc = fast_exp2((isk ? -1.f : 1.f) * (float)(t & 127) * lg2gamma(h)) * rs;
;           const f32x4 x1 = acc[ai][bj][m][0] * sc, x2 = acc[ai][bj][m][1] * sc;
;           const f32x4 y1 = x1 * cs - x2 * sn, y2 = x2 * cs + x1 * sn;
;           const int d = 16 * wc + 4 * fq;
;           const int tl2 = t & 127, r32 = tl2 & 31;
;           const int frag = isk ? (((tl2 >> 5) * 2 + ((r32 >> 2) & 1)) * 4 + (d >> 5)) : ((tl2 >> 4) * 4 + (d >> 5));
;           const int frl = isk ? ((r32 >> 3) * 4 + (r32 & 3)) : (tl2 & 15);
;           bf16_t* dst = dstb + ((long)((b * 4 + h) * 64 + (t >> 7))) * 16384 + (frag * 64 + ((d >> 3) & 3) * 16 + frl) * 8 + (d & 7);
;           const u32x2 o1 = pk4(y1), o2 = pk4(y2);
;           *(u32x2*)dst = o1; *(u32x2*)(dst + 2 * 512) = o2;
;           if (isk) {
;             LAS unsigned char* tb = shm + 135168 + wid * 1024;
;             LAS bf16_t* w1 = (LAS bf16_t*)(tb + (4 * fq) * 32 + fr * 2);
;             w1[0] = (bf16_t)(o1.x & 0xffff); w1[16] = (bf16_t)(o1.x >> 16); w1[32] = (bf16_t)(o1.y & 0xffff); w1[48] = (bf16_t)(o1.y >> 16);
;             LAS bf16_t* w2 = w1 + 16 * 16;
;             w2[0] = (bf16_t)(o2.x & 0xffff); w2[16] = (bf16_t)(o2.x >> 16); w2[32] = (bf16_t)(o2.y & 0xffff); w2[48] = (bf16_t)(o2.y >> 16);
;             asm volatile("s_waitcnt lgkmcnt(0)" ::: "memory");
;             const int dl = lane >> 1, th = lane & 1;
;             const u32x4 kv = *(const LAS u32x4*)(tb + dl * 32 + th * 16);
;             asm volatile("" ::: "memory");
;             const int dd = dl < 16 ? 16 * wc + dl : 48 + 16 * wc + dl;
;             const int tb0 = t0 + 128 * ai + 64 * wr + 16 * m + 8 * th, tl = tb0 & 127;
;             *(u32x4*)(krt + ((long)((b * 4 + h) * 64 + (tb0 >> 7))) * 16384 + (((dd >> 4) * 4 + (tl >> 5)) * 64 + ((tl >> 3) & 3) * 16 + (dd & 15)) * 8) = kv;
.LBB0_385:
	v_add_u32_e32 v56, 0x90, v176
	v_or_b32_e32 v57, v56, v168
	v_add_u32_e32 v58, s59, v57
	v_lshlrev_b32_e32 v48, 6, v58
	v_ashrrev_i32_e32 v49, 31, v48
	v_lshlrev_b64 v[48:49], 2, v[48:49]
	v_lshl_add_u64 v[50:51], v[154:155], 0, v[48:49]
	v_lshl_add_u64 v[48:49], v[152:153], 0, v[48:49]
	v_add_u32_e32 v251, 0x1000, v251
	global_load_dwordx4 v[238:241], v251, s[20:21]
	global_load_dwordx4 v[242:245], v251, s[16:17]
	v_bitop3_b32 v59, v56, s91, v168 bitop3:0xc8
	v_lshrrev_b32_e32 v56, 2, v56
	v_cvt_f32_ubyte0_e32 v59, v59
	v_lshrrev_b32_e32 v60, 1, v57
	v_and_or_b32 v61, v56, 20, v174
	v_and_or_b32 v62, v56, 16, v175
	v_cndmask_b32_e64 v57, v59, -v59, s[6:7]
	v_and_or_b32 v59, v60, 12, v173
	v_cndmask_b32_e64 v60, v61, v62, s[6:7]
	v_mul_f32_e32 v61, v177, v57
	v_exp_f32_e32 v61, v61
	v_cndmask_b32_e64 v59, v168, v59, s[6:7]
	v_ashrrev_i32_e32 v56, 7, v58
	v_lshlrev_b32_e32 v60, 9, v60
	v_or_b32_e32 v62, v59, v172
	v_add_u32_e32 v58, s58, v56
	v_lshl_or_b32 v60, v62, 3, v60
	v_ashrrev_i32_e32 v59, 31, v58
	v_lshlrev_b32_e32 v148, 1, v60
	v_mul_f32_e32 v60, v65, v61
	v_lshlrev_b64 v[58:59], 15, v[58:59]
	v_pk_mul_f32 v[46:47], v[46:47], v[60:61] op_sel_hi:[1,0]
	v_pk_mul_f32 v[44:45], v[44:45], v[60:61] op_sel_hi:[1,0]
	v_pk_mul_f32 v[42:43], v[42:43], v[60:61] op_sel_hi:[1,0]
	v_pk_mul_f32 v[40:41], v[40:41], v[60:61] op_sel_hi:[1,0]
	v_lshl_add_u64 v[58:59], s[56:57], 0, v[58:59]
	v_mov_b32_e32 v125, v149
	v_lshl_add_u64 v[58:59], v[58:59], 0, v[148:149]
	s_and_b64 vcc, exec, s[8:9]
	v_lshl_add_u64 v[58:59], v[58:59], 0, v[124:125]
	s_waitcnt vmcnt(7)
	v_pk_mul_f32 v[60:61], v[42:43], v[248:249]
	v_pk_mul_f32 v[62:63], v[40:41], v[246:247]
	v_pk_mul_f32 v[68:69], v[46:47], v[248:249]
	v_pk_mul_f32 v[70:71], v[44:45], v[246:247]
	s_waitcnt vmcnt(6)
	v_pk_fma_f32 v[46:47], v[46:47], v[254:255], v[60:61] neg_lo:[0,0,1] neg_hi:[0,0,1]
	v_pk_fma_f32 v[44:45], v[44:45], v[252:253], v[62:63] neg_lo:[0,0,1] neg_hi:[0,0,1]
	v_pk_fma_f32 v[60:61], v[42:43], v[254:255], v[68:69]
	v_pk_fma_f32 v[40:41], v[40:41], v[252:253], v[70:71]
	v_cvt_pk_bf16_f32 v42, v44, v45
	v_cvt_pk_bf16_f32 v43, v46, v47
	v_cvt_pk_bf16_f32 v40, v40, v41
	v_cvt_pk_bf16_f32 v41, v60, v61
	global_store_dwordx2 v[58:59], v[42:43], off
	global_store_dwordx2 v[58:59], v[40:41], off offset:2048
	s_cbranch_vccnz .LBB0_387
	ds_write_b16 v169, v42
	ds_write_b16_d16_hi v169, v42 offset:32
	ds_write_b16 v169, v43 offset:64
	ds_write_b16_d16_hi v169, v43 offset:96
	ds_write_b16 v169, v40 offset:512
	ds_write_b16_d16_hi v169, v40 offset:544
	ds_write_b16 v169, v41 offset:576
	ds_write_b16_d16_hi v169, v41 offset:608
	s_waitcnt lgkmcnt(0)
	v_add_u32_e32 v40, v170, v171
	ds_read_b128 v[40:43], v40
	v_add_u32_e32 v44, s58, v76
	v_ashrrev_i32_e32 v45, 31, v44
	v_lshlrev_b64 v[44:45], 15, v[44:45]
	v_lshl_add_u64 v[44:45], v[156:157], 0, v[44:45]
	s_waitcnt lgkmcnt(0)
	global_store_dwordx4 v[44:45], v[40:43], off offset:512 nt
.LBB0_387:
	s_nop 1
	v_mul_f32_e32 v40, v126, v57
	v_exp_f32_e32 v40, v40
	s_and_b64 vcc, exec, s[8:9]
	v_mul_f32_e32 v40, v65, v40
	v_pk_mul_f32 v[34:35], v[34:35], v[40:41] op_sel_hi:[1,0]
	v_pk_mul_f32 v[38:39], v[38:39], v[40:41] op_sel_hi:[1,0]
	v_pk_mul_f32 v[36:37], v[36:37], v[40:41] op_sel_hi:[1,0]
	v_pk_mul_f32 v[32:33], v[32:33], v[40:41] op_sel_hi:[1,0]
	v_pk_mul_f32 v[40:41], v[34:35], v[248:249]
	v_pk_mul_f32 v[42:43], v[32:33], v[246:247]
	v_pk_fma_f32 v[40:41], v[38:39], v[254:255], v[40:41] neg_lo:[0,0,1] neg_hi:[0,0,1]
	v_pk_mul_f32 v[38:39], v[38:39], v[248:249]
	v_pk_fma_f32 v[42:43], v[36:37], v[252:253], v[42:43] neg_lo:[0,0,1] neg_hi:[0,0,1]
	v_pk_fma_f32 v[38:39], v[34:35], v[254:255], v[38:39]
	v_add_u32_e32 v34, s0, v56
	v_ashrrev_i32_e32 v35, 31, v34
	v_lshlrev_b64 v[34:35], 15, v[34:35]
	v_pk_mul_f32 v[36:37], v[36:37], v[246:247]
	v_lshl_add_u64 v[34:35], s[56:57], 0, v[34:35]
	v_pk_fma_f32 v[32:33], v[32:33], v[252:253], v[36:37]
	v_lshl_add_u64 v[34:35], v[34:35], 0, v[148:149]
	v_lshl_add_u64 v[36:37], v[34:35], 0, v[124:125]
	v_cvt_pk_bf16_f32 v34, v42, v43
	v_cvt_pk_bf16_f32 v35, v40, v41
	v_cvt_pk_bf16_f32 v32, v32, v33
	v_cvt_pk_bf16_f32 v33, v38, v39
	v_mov_b32_e32 v40, v174
	global_store_dwordx2 v[36:37], v[34:35], off
	global_store_dwordx2 v[36:37], v[32:33], off offset:2048
	s_cbranch_vccnz .LBB0_389
	ds_write_b16 v169, v34
	ds_write_b16_d16_hi v169, v34 offset:32
	ds_write_b16 v169, v35 offset:64
	ds_write_b16_d16_hi v169, v35 offset:96
	ds_write_b16 v169, v32 offset:512
	ds_write_b16_d16_hi v169, v32 offset:544
	ds_write_b16 v169, v33 offset:576
	ds_write_b16_d16_hi v169, v33 offset:608
	s_waitcnt lgkmcnt(0)
	v_add_u32_e32 v32, v170, v171
	ds_read_b128 v[32:35], v32
	v_add_u32_e32 v36, s0, v76
	v_ashrrev_i32_e32 v37, 31, v36
	v_lshlrev_b64 v[36:37], 15, v[36:37]
	v_lshl_add_u64 v[36:37], v[156:157], 0, v[36:37]
	v_mov_b32_e32 v40, v175
	s_waitcnt lgkmcnt(0)
	global_store_dwordx4 v[36:37], v[32:35], off offset:512 nt
; template <int REG>
; DI void epi_inproj(const Params& p, f32x4 (&acc)[2][2][4][2], int pm, int pn, LAS unsigned char* shm) {
;     ...
;       for (int m = 0; m < 4; ++m) { asm volatile("" ::: "memory");
;         const int r = 128 * ai + 64 * wr + 16 * m + fr, t = t0 + r;
;         const float rs = rsr[ai][m];
;         const f32x4 cs = *(const f32x4*)(cosT + t * 64 + 16 * wc + 4 * fq), sn = *(const f32x4*)(sinT + t * 64 + 16 * wc + 4 * fq);
; #pragma unroll
;         for (int bj = 0; bj < 2; ++bj) {
;           const int h = 2 * (pn & 1) + bj;
;           const float sc = fast_exp2((isk ? -1.f : 1.f) * (float)(t & 127) * lg2gamma(h)) * rs;
;           const f32x4 x1 = acc[ai][bj][m][0] * sc, x2 = acc[ai][bj][m][1] * sc;
;           const f32x4 y1 = x1 * cs - x2 * sn, y2 = x2 * cs + x1 * sn;
;           const int d = 16 * wc + 4 * fq;
;           const int tl2 = t & 127, r32 = tl2 & 31;
;           const int frag = isk ? (((tl2 >> 5) * 2 + ((r32 >> 2) & 1)) * 4 + (d >> 5)) : ((tl2 >> 4) * 4 + (d >> 5));
;           const int frl = isk ? ((r32 >> 3) * 4 + (r32 & 3)) : (tl2 & 15);
;           bf16_t* dst = dstb + ((long)((b * 4 + h) * 64 + (t >> 7))) * 16384 + (frag * 64 + ((d >> 3) & 3) * 16 + frl) * 8 + (d & 7);
;           const u32x2 o1 = pk4(y1), o2 = pk4(y2);
;           *(u32x2*)dst = o1; *(u32x2*)(dst + 2 * 512) = o2;
;           if (isk) {
;             LAS unsigned char* tb = shm + 135168 + wid * 1024;
;             LAS bf16_t* w1 = (LAS bf16_t*)(tb + (4 * fq) * 32 + fr * 2);
;             w1[0] = (bf16_t)(o1.x & 0xffff); w1[16] = (bf16_t)(o1.x >> 16); w1[32] = (bf16_t)(o1.y & 0xffff); w1[48] = (bf16_t)(o1.y >> 16);
;             LAS bf16_t* w2 = w1 + 16 * 16;
;             w2[0] = (bf16_t)(o2.x & 0xffff); w2[16] = (bf16_t)(o2.x >> 16); w2[32] = (bf16_t)(o2.y & 0xffff); w2[48] = (bf16_t)(o2.y >> 16);
;             asm volatile("s_waitcnt lgkmcnt(0)" ::: "memory");
;             const int dl = lane >> 1, th = lane & 1;
;             const u32x4 kv = *(const LAS u32x4*)(tb + dl * 32 + th * 16);
;             asm volatile("" ::: "memory");
;             const int dd = dl < 16 ? 16 * wc + dl : 48 + 16 * wc + dl;
;             const int tb0 = t0 + 128 * ai + 64 * wr + 16 * m + 8 * th, tl = tb0 & 127;
;             *(u32x4*)(krt + ((long)((b * 4 + h) * 64 + (tb0 >> 7))) * 16384 + (((dd >> 4) * 4 + (tl >> 5)) * 64 + ((tl >> 3) & 3) * 16 + (dd & 15)) * 8) = kv;
.LBB0_389:
	v_add_u32_e32 v41, 0xa0, v176
	s_nop 0
	v_or_b32_e32 v32, v41, v168
	v_add_u32_e32 v42, s59, v32
	v_lshlrev_b32_e32 v32, 6, v42
	v_ashrrev_i32_e32 v33, 31, v32
	v_lshlrev_b64 v[32:33], 2, v[32:33]
	v_lshl_add_u64 v[34:35], v[154:155], 0, v[32:33]
	v_lshl_add_u64 v[32:33], v[152:153], 0, v[32:33]
	v_add_u32_e32 v251, 0x1000, v251
	global_load_dwordx4 v[246:249], v251, s[20:21]
	global_load_dwordx4 v[252:255], v251, s[16:17]
	v_bitop3_b32 v43, v41, s92, v168 bitop3:0xc8
	v_lshrrev_b32_e32 v41, 2, v41
	v_cvt_f32_ubyte0_e32 v43, v43
	v_and_or_b32 v44, v41, 24, v40
	v_cndmask_b32_e64 v41, v43, -v43, s[6:7]
	v_lshl_or_b32 v43, v44, 9, v130
	v_mul_f32_e32 v44, v177, v41
	v_exp_f32_e32 v44, v44
	v_ashrrev_i32_e32 v40, 7, v42
	v_add_u32_e32 v42, s58, v40
	v_lshlrev_b32_e32 v148, 1, v43
	v_ashrrev_i32_e32 v43, 31, v42
	v_mul_f32_e32 v44, v66, v44
	v_lshlrev_b64 v[42:43], 15, v[42:43]
	v_pk_mul_f32 v[30:31], v[30:31], v[44:45] op_sel_hi:[1,0]
	v_pk_mul_f32 v[28:29], v[28:29], v[44:45] op_sel_hi:[1,0]
	v_pk_mul_f32 v[26:27], v[26:27], v[44:45] op_sel_hi:[1,0]
	v_pk_mul_f32 v[24:25], v[24:25], v[44:45] op_sel_hi:[1,0]
	v_lshl_add_u64 v[42:43], s[56:57], 0, v[42:43]
	v_mov_b32_e32 v125, v149
	v_lshl_add_u64 v[42:43], v[42:43], 0, v[148:149]
	s_and_b64 vcc, exec, s[8:9]
	v_lshl_add_u64 v[42:43], v[42:43], 0, v[124:125]
	s_waitcnt vmcnt(7)
	v_pk_mul_f32 v[44:45], v[26:27], v[240:241]
	v_pk_mul_f32 v[46:47], v[24:25], v[238:239]
	v_pk_mul_f32 v[48:49], v[30:31], v[240:241]
	v_pk_mul_f32 v[50:51], v[28:29], v[238:239]
	s_waitcnt vmcnt(6)
	v_pk_fma_f32 v[30:31], v[30:31], v[244:245], v[44:45] neg_lo:[0,0,1] neg_hi:[0,0,1]
	v_pk_fma_f32 v[28:29], v[28:29], v[242:243], v[46:47] neg_lo:[0,0,1] neg_hi:[0,0,1]
	v_pk_fma_f32 v[44:45], v[26:27], v[244:245], v[48:49]
	v_pk_fma_f32 v[24:25], v[24:25], v[242:243], v[50:51]
	v_cvt_pk_bf16_f32 v26, v28, v29
	v_cvt_pk_bf16_f32 v27, v30, v31
	v_cvt_pk_bf16_f32 v24, v24, v25
	v_cvt_pk_bf16_f32 v25, v44, v45
	global_store_dwordx2 v[42:43], v[26:27], off
	global_store_dwordx2 v[42:43], v[24:25], off offset:2048
	s_cbranch_vccnz .LBB0_391
	ds_write_b16 v169, v26
	ds_write_b16_d16_hi v169, v26 offset:32
	ds_write_b16 v169, v27 offset:64
	ds_write_b16_d16_hi v169, v27 offset:96
	ds_write_b16 v169, v24 offset:512
	ds_write_b16_d16_hi v169, v24 offset:544
	ds_write_b16 v169, v25 offset:576
	ds_write_b16_d16_hi v169, v25 offset:608
	s_waitcnt lgkmcnt(0)
	v_add_u32_e32 v24, v170, v171
	ds_read_b128 v[24:27], v24
	v_add_u32_e32 v28, s58, v76
	v_ashrrev_i32_e32 v29, 31, v28
	v_lshlrev_b64 v[28:29], 15, v[28:29]
	v_lshl_add_u64 v[28:29], v[108:109], 0, v[28:29]
	s_waitcnt lgkmcnt(0)
	global_store_dwordx4 v[28:29], v[24:27], off nt
.LBB0_391:
	s_nop 1
	v_mul_f32_e32 v24, v126, v41
	v_exp_f32_e32 v24, v24
	s_and_b64 vcc, exec, s[8:9]
	v_mul_f32_e32 v24, v66, v24
	v_pk_mul_f32 v[18:19], v[18:19], v[24:25] op_sel_hi:[1,0]
	v_pk_mul_f32 v[22:23], v[22:23], v[24:25] op_sel_hi:[1,0]
	v_pk_mul_f32 v[20:21], v[20:21], v[24:25] op_sel_hi:[1,0]
	v_pk_mul_f32 v[16:17], v[16:17], v[24:25] op_sel_hi:[1,0]
	v_pk_mul_f32 v[24:25], v[18:19], v[240:241]
	v_pk_mul_f32 v[26:27], v[16:17], v[238:239]
	v_pk_fma_f32 v[24:25], v[22:23], v[244:245], v[24:25] neg_lo:[0,0,1] neg_hi:[0,0,1]
	v_pk_mul_f32 v[22:23], v[22:23], v[240:241]
	v_pk_fma_f32 v[26:27], v[20:21], v[242:243], v[26:27] neg_lo:[0,0,1] neg_hi:[0,0,1]
	v_pk_fma_f32 v[22:23], v[18:19], v[244:245], v[22:23]
	v_add_u32_e32 v18, s0, v40
	v_ashrrev_i32_e32 v19, 31, v18
	v_lshlrev_b64 v[18:19], 15, v[18:19]
	v_pk_mul_f32 v[20:21], v[20:21], v[238:239]
	v_lshl_add_u64 v[18:19], s[56:57], 0, v[18:19]
	v_pk_fma_f32 v[16:17], v[16:17], v[242:243], v[20:21]
	v_lshl_add_u64 v[18:19], v[18:19], 0, v[148:149]
	v_lshl_add_u64 v[20:21], v[18:19], 0, v[124:125]
	v_cvt_pk_bf16_f32 v18, v26, v27
	v_cvt_pk_bf16_f32 v19, v24, v25
	v_cvt_pk_bf16_f32 v16, v16, v17
	v_cvt_pk_bf16_f32 v17, v22, v23
	global_store_dwordx2 v[20:21], v[18:19], off
	global_store_dwordx2 v[20:21], v[16:17], off offset:2048
	s_cbranch_vccnz .LBB0_393
	ds_write_b16 v169, v18
	ds_write_b16_d16_hi v169, v18 offset:32
	ds_write_b16 v169, v19 offset:64
	ds_write_b16_d16_hi v169, v19 offset:96
	ds_write_b16 v169, v16 offset:512
	ds_write_b16_d16_hi v169, v16 offset:544
	ds_write_b16 v169, v17 offset:576
	ds_write_b16_d16_hi v169, v17 offset:608
	s_waitcnt lgkmcnt(0)
	v_add_u32_e32 v16, v170, v171
	ds_read_b128 v[16:19], v16
	v_add_u32_e32 v20, s0, v76
	v_ashrrev_i32_e32 v21, 31, v20
	v_lshlrev_b64 v[20:21], 15, v[20:21]
	v_lshl_add_u64 v[20:21], v[108:109], 0, v[20:21]
	s_waitcnt lgkmcnt(0)
	global_store_dwordx4 v[20:21], v[16:19], off nt
; template <int REG>
; DI void epi_inproj(const Params& p, f32x4 (&acc)[2][2][4][2], int pm, int pn, LAS unsigned char* shm) {
;     ...
;       for (int m = 0; m < 4; ++m) { asm volatile("" ::: "memory");
;         const int r = 128 * ai + 64 * wr + 16 * m + fr, t = t0 + r;
;         const float rs = rsr[ai][m];
;         const f32x4 cs = *(const f32x4*)(cosT + t * 64 + 16 * wc + 4 * fq), sn = *(const f32x4*)(sinT + t * 64 + 16 * wc + 4 * fq);
; #pragma unroll
;         for (int bj = 0; bj < 2; ++bj) {
;           const int h = 2 * (pn & 1) + bj;
;           const float sc = fast_exp2((isk ? -1.f : 1.f) * (float)(t & 127) * lg2gamma(h)) * rs;
;           const f32x4 x1 = acc[ai][bj][m][0] * sc, x2 = acc[ai][bj][m][1] * sc;
;           const f32x4 y1 = x1 * cs - x2 * sn, y2 = x2 * cs + x1 * sn;
;           const int d = 16 * wc + 4 * fq;
;           const int tl2 = t & 127, r32 = tl2 & 31;
;           const int frag = isk ? (((tl2 >> 5) * 2 + ((r32 >> 2) & 1)) * 4 + (d >> 5)) : ((tl2 >> 4) * 4 + (d >> 5));
;           const int frl = isk ? ((r32 >> 3) * 4 + (r32 & 3)) : (tl2 & 15);
;           bf16_t* dst = dstb + ((long)((b * 4 + h) * 64 + (t >> 7))) * 16384 + (frag * 64 + ((d >> 3) & 3) * 16 + frl) * 8 + (d & 7);
;           const u32x2 o1 = pk4(y1), o2 = pk4(y2);
;           *(u32x2*)dst = o1; *(u32x2*)(dst + 2 * 512) = o2;
;           if (isk) {
;             LAS unsigned char* tb = shm + 135168 + wid * 1024;
;             LAS bf16_t* w1 = (LAS bf16_t*)(tb + (4 * fq) * 32 + fr * 2);
;             w1[0] = (bf16_t)(o1.x & 0xffff); w1[16] = (bf16_t)(o1.x >> 16); w1[32] = (bf16_t)(o1.y & 0xffff); w1[48] = (bf16_t)(o1.y >> 16);
;             LAS bf16_t* w2 = w1 + 16 * 16;
;             w2[0] = (bf16_t)(o2.x & 0xffff); w2[16] = (bf16_t)(o2.x >> 16); w2[32] = (bf16_t)(o2.y & 0xffff); w2[48] = (bf16_t)(o2.y >> 16);
;             asm volatile("s_waitcnt lgkmcnt(0)" ::: "memory");
;             const int dl = lane >> 1, th = lane & 1;
;             const u32x4 kv = *(const LAS u32x4*)(tb + dl * 32 + th * 16);
;             asm volatile("" ::: "memory");
;             const int dd = dl < 16 ? 16 * wc + dl : 48 + 16 * wc + dl;
;             const int tb0 = t0 + 128 * ai + 64 * wr + 16 * m + 8 * th, tl = tb0 & 127;
;             *(u32x4*)(krt + ((long)((b * 4 + h) * 64 + (tb0 >> 7))) * 16384 + (((dd >> 4) * 4 + (tl >> 5)) * 64 + ((tl >> 3) & 3) * 16 + (dd & 15)) * 8) = kv;
.LBB0_393:
	v_add_u32_e32 v24, 0xb0, v176
	v_or_b32_e32 v25, v24, v168
	v_add_u32_e32 v26, s59, v25
	v_lshlrev_b32_e32 v16, 6, v26
	v_ashrrev_i32_e32 v17, 31, v16
	v_lshlrev_b64 v[16:17], 2, v[16:17]
	v_lshl_add_u64 v[18:19], v[154:155], 0, v[16:17]
	v_lshl_add_u64 v[16:17], v[152:153], 0, v[16:17]
	v_bitop3_b32 v27, v24, s93, v168 bitop3:0xc8
	v_lshrrev_b32_e32 v24, 2, v24
	v_cvt_f32_ubyte0_e32 v27, v27
	v_lshrrev_b32_e32 v28, 1, v25
	v_and_or_b32 v29, v24, 28, v174
	v_and_or_b32 v30, v24, 24, v175
	v_cndmask_b32_e64 v25, v27, -v27, s[6:7]
	v_and_or_b32 v27, v28, 12, v173
	v_cndmask_b32_e64 v28, v29, v30, s[6:7]
	v_mul_f32_e32 v29, v177, v25
	v_exp_f32_e32 v29, v29
	v_cndmask_b32_e64 v27, v168, v27, s[6:7]
	v_ashrrev_i32_e32 v24, 7, v26
	v_lshlrev_b32_e32 v28, 9, v28
	v_or_b32_e32 v30, v27, v172
	v_add_u32_e32 v26, s58, v24
	v_lshl_or_b32 v28, v30, 3, v28
	v_ashrrev_i32_e32 v27, 31, v26
	v_lshlrev_b32_e32 v148, 1, v28
	v_mul_f32_e32 v28, v67, v29
	v_lshlrev_b64 v[26:27], 15, v[26:27]
	v_pk_mul_f32 v[14:15], v[14:15], v[28:29] op_sel_hi:[1,0]
	v_pk_mul_f32 v[12:13], v[12:13], v[28:29] op_sel_hi:[1,0]
	v_pk_mul_f32 v[10:11], v[10:11], v[28:29] op_sel_hi:[1,0]
	v_pk_mul_f32 v[8:9], v[8:9], v[28:29] op_sel_hi:[1,0]
	v_lshl_add_u64 v[26:27], s[56:57], 0, v[26:27]
	v_mov_b32_e32 v125, v149
	v_lshl_add_u64 v[26:27], v[26:27], 0, v[148:149]
	s_and_b64 vcc, exec, s[8:9]
	v_lshl_add_u64 v[26:27], v[26:27], 0, v[124:125]
	s_waitcnt vmcnt(5)
	v_pk_mul_f32 v[28:29], v[10:11], v[248:249]
	v_pk_mul_f32 v[30:31], v[8:9], v[246:247]
	v_pk_mul_f32 v[32:33], v[14:15], v[248:249]
	v_pk_mul_f32 v[34:35], v[12:13], v[246:247]
	s_waitcnt vmcnt(4)
	v_pk_fma_f32 v[14:15], v[14:15], v[254:255], v[28:29] neg_lo:[0,0,1] neg_hi:[0,0,1]
	v_pk_fma_f32 v[12:13], v[12:13], v[252:253], v[30:31] neg_lo:[0,0,1] neg_hi:[0,0,1]
	v_pk_fma_f32 v[28:29], v[10:11], v[254:255], v[32:33]
	v_pk_fma_f32 v[8:9], v[8:9], v[252:253], v[34:35]
	v_cvt_pk_bf16_f32 v10, v12, v13
	v_cvt_pk_bf16_f32 v11, v14, v15
	v_cvt_pk_bf16_f32 v8, v8, v9
	v_cvt_pk_bf16_f32 v9, v28, v29
	global_store_dwordx2 v[26:27], v[10:11], off
	global_store_dwordx2 v[26:27], v[8:9], off offset:2048
	s_cbranch_vccnz .LBB0_395
	ds_write_b16 v169, v10
	ds_write_b16_d16_hi v169, v10 offset:32
	ds_write_b16 v169, v11 offset:64
	ds_write_b16_d16_hi v169, v11 offset:96
	ds_write_b16 v169, v8 offset:512
	ds_write_b16_d16_hi v169, v8 offset:544
	ds_write_b16 v169, v9 offset:576
	ds_write_b16_d16_hi v169, v9 offset:608
	s_waitcnt lgkmcnt(0)
	v_add_u32_e32 v8, v170, v171
	ds_read_b128 v[8:11], v8
	v_add_u32_e32 v12, s58, v76
	v_ashrrev_i32_e32 v13, 31, v12
	v_lshlrev_b64 v[12:13], 15, v[12:13]
	v_lshl_add_u64 v[12:13], v[92:93], 0, v[12:13]
	s_waitcnt lgkmcnt(0)
	global_store_dwordx4 v[12:13], v[8:11], off nt
.LBB0_395:
	s_nop 1
	v_mul_f32_e32 v8, v126, v25
	v_exp_f32_e32 v8, v8
	s_and_b64 vcc, exec, s[8:9]
	v_mul_f32_e32 v8, v67, v8
	v_pk_mul_f32 v[2:3], v[2:3], v[8:9] op_sel_hi:[1,0]
	v_pk_mul_f32 v[6:7], v[6:7], v[8:9] op_sel_hi:[1,0]
	v_pk_mul_f32 v[4:5], v[4:5], v[8:9] op_sel_hi:[1,0]
	v_pk_mul_f32 v[0:1], v[0:1], v[8:9] op_sel_hi:[1,0]
	v_pk_mul_f32 v[8:9], v[2:3], v[248:249]
	v_pk_mul_f32 v[10:11], v[0:1], v[246:247]
	v_pk_fma_f32 v[8:9], v[6:7], v[254:255], v[8:9] neg_lo:[0,0,1] neg_hi:[0,0,1]
	v_pk_mul_f32 v[6:7], v[6:7], v[248:249]
	v_pk_fma_f32 v[10:11], v[4:5], v[252:253], v[10:11] neg_lo:[0,0,1] neg_hi:[0,0,1]
	v_pk_fma_f32 v[6:7], v[2:3], v[254:255], v[6:7]
	v_add_u32_e32 v2, s0, v24
	v_ashrrev_i32_e32 v3, 31, v2
	v_lshlrev_b64 v[2:3], 15, v[2:3]
	v_pk_mul_f32 v[4:5], v[4:5], v[246:247]
	v_lshl_add_u64 v[2:3], s[56:57], 0, v[2:3]
	v_pk_fma_f32 v[0:1], v[0:1], v[252:253], v[4:5]
	v_lshl_add_u64 v[2:3], v[2:3], 0, v[148:149]
	v_lshl_add_u64 v[4:5], v[2:3], 0, v[124:125]
	v_cvt_pk_bf16_f32 v2, v10, v11
	v_cvt_pk_bf16_f32 v3, v8, v9
	v_cvt_pk_bf16_f32 v0, v0, v1
	v_cvt_pk_bf16_f32 v1, v6, v7
	global_store_dwordx2 v[4:5], v[2:3], off
	global_store_dwordx2 v[4:5], v[0:1], off offset:2048
	s_cbranch_vccnz .LBB0_397
	ds_write_b16 v169, v2
	ds_write_b16_d16_hi v169, v2 offset:32
	ds_write_b16 v169, v3 offset:64
	ds_write_b16_d16_hi v169, v3 offset:96
	ds_write_b16 v169, v0 offset:512
	ds_write_b16_d16_hi v169, v0 offset:544
	ds_write_b16 v169, v1 offset:576
	ds_write_b16_d16_hi v169, v1 offset:608
	s_waitcnt lgkmcnt(0)
	v_add_u32_e32 v0, v170, v171
	ds_read_b128 v[0:3], v0
	v_add_u32_e32 v4, s0, v76
	v_ashrrev_i32_e32 v5, 31, v4
	v_lshlrev_b64 v[4:5], 15, v[4:5]
	v_lshl_add_u64 v[4:5], v[92:93], 0, v[4:5]
	s_waitcnt lgkmcnt(0)
	global_store_dwordx4 v[4:5], v[0:3], off nt
